# nt (streaming) hint on the 32 final f32 output stores of the last down-projection epilogue
# speedup vs baseline: 1.0024x; 1.0024x over previous
;     __device__ __forceinline__ void operator()(f32x4 (&acc)[2][2][4][2], const Unit& u, int wr, int wc, int fr, int fq) const {
;     ...
;         asm volatile("s_waitcnt lgkmcnt(0)" ::: "memory"); __builtin_amdgcn_s_barrier(); asm volatile("" ::: "memory");
;         f32x4 gg[2][2];
; #pragma unroll
;         for (int bj = 0; bj < 2; ++bj) { gg[bj][0] = *(const f32x4*)(gfin + col0 + bj * HALF); gg[bj][1] = *(const f32x4*)(gfin + col0 + bj * HALF + 4); }
; #pragma unroll
;         for (int ai = 0; ai < 2; ++ai)
; #pragma unroll
;             for (int m = 0; m < 4; ++m) { const int rl = ai * HALF + wr * 64 + m * 16 + fr; const float rs = rstab[rl]; float* orow = out + (size_t)(u.pm * BM + rl) * D + col0;
; #pragma unroll
;                 for (int bj = 0; bj < 2; ++bj) { *(f32x4*)(orow + bj * HALF) = acc[ai][bj][m][0] * gg[bj][0] * rs; *(f32x4*)(orow + bj * HALF + 4) = acc[ai][bj][m][1] * gg[bj][1] * rs; } }
.LBB0_238:
	s_or_b64 exec, exec, s[4:5]
	v_readlane_b32 s4, v255, 0
	v_lshlrev_b64 v[146:147], 2, v[204:205]
	v_readlane_b32 s5, v255, 1
	s_waitcnt lgkmcnt(0)
	s_barrier
	v_lshlrev_b64 v[148:149], 12, v[202:203]
	v_lshl_add_u64 v[2:3], s[4:5], 0, v[146:147]
	flat_load_dwordx4 v[14:17], v[2:3]
	flat_load_dwordx4 v[10:13], v[2:3] offset:16
	flat_load_dwordx4 v[6:9], v[2:3] offset:512
	s_nop 0
	flat_load_dwordx4 v[2:5], v[2:3] offset:528
	ds_read_b32 v156, v217
	v_lshl_add_u64 v[148:149], s[34:35], 0, v[148:149]
	v_lshl_add_u64 v[148:149], v[148:149], 0, v[146:147]
	v_add_u32_e32 v150, s51, v210
	v_ashrrev_i32_e32 v151, 31, v150
	v_lshlrev_b64 v[150:151], 12, v[150:151]
	v_lshl_add_u64 v[150:151], s[34:35], 0, v[150:151]
	v_lshl_add_u64 v[150:151], v[150:151], 0, v[146:147]
	v_add_u32_e32 v152, s51, v211
	v_ashrrev_i32_e32 v153, 31, v152
	v_lshlrev_b64 v[152:153], 12, v[152:153]
	v_lshl_add_u64 v[152:153], s[34:35], 0, v[152:153]
	v_lshl_add_u64 v[152:153], v[152:153], 0, v[146:147]
	v_add_u32_e32 v154, s51, v212
	v_ashrrev_i32_e32 v155, 31, v154
	v_lshlrev_b64 v[154:155], 12, v[154:155]
	v_lshl_add_u64 v[154:155], s[34:35], 0, v[154:155]
	v_lshl_add_u64 v[154:155], v[154:155], 0, v[146:147]
	s_and_b64 vcc, exec, s[8:9]
	s_mov_b64 s[4:5], -1
	s_waitcnt vmcnt(0) lgkmcnt(0)
	v_pk_mul_f32 v[128:129], v[128:129], v[16:17]
	v_pk_mul_f32 v[126:127], v[126:127], v[14:15]
	v_pk_mul_f32 v[124:125], v[124:125], v[12:13]
	v_pk_mul_f32 v[122:123], v[122:123], v[10:11]
	v_pk_mul_f32 v[120:121], v[120:121], v[8:9]
	v_pk_mul_f32 v[118:119], v[118:119], v[6:7]
	v_pk_mul_f32 v[116:117], v[116:117], v[4:5]
	v_pk_mul_f32 v[114:115], v[114:115], v[2:3]
	v_pk_mul_f32 v[170:171], v[96:97], v[16:17]
	v_pk_mul_f32 v[172:173], v[94:95], v[14:15]
	v_pk_mul_f32 v[94:95], v[126:127], v[156:157] op_sel_hi:[1,0]
	v_pk_mul_f32 v[96:97], v[128:129], v[156:157] op_sel_hi:[1,0]
	v_pk_mul_f32 v[158:159], v[108:109], v[12:13]
	v_pk_mul_f32 v[160:161], v[106:107], v[10:11]
	v_pk_mul_f32 v[162:163], v[104:105], v[8:9]
	v_pk_mul_f32 v[164:165], v[102:103], v[6:7]
	v_pk_mul_f32 v[166:167], v[100:101], v[4:5]
	v_pk_mul_f32 v[168:169], v[98:99], v[2:3]
	v_pk_mul_f32 v[98:99], v[122:123], v[156:157] op_sel_hi:[1,0]
	v_pk_mul_f32 v[100:101], v[124:125], v[156:157] op_sel_hi:[1,0]
	v_pk_mul_f32 v[102:103], v[118:119], v[156:157] op_sel_hi:[1,0]
	v_pk_mul_f32 v[104:105], v[120:121], v[156:157] op_sel_hi:[1,0]
	v_pk_mul_f32 v[106:107], v[114:115], v[156:157] op_sel_hi:[1,0]
	v_pk_mul_f32 v[108:109], v[116:117], v[156:157] op_sel_hi:[1,0]
	flat_store_dwordx4 v[148:149], v[94:97] nt
	flat_store_dwordx4 v[148:149], v[98:101] offset:16 nt
	flat_store_dwordx4 v[148:149], v[102:105] offset:512 nt
	flat_store_dwordx4 v[148:149], v[106:109] offset:528 nt
	ds_read_b32 v98, v218
	v_pk_mul_f32 v[112:113], v[112:113], v[16:17]
	v_pk_mul_f32 v[110:111], v[110:111], v[14:15]
	v_pk_mul_f32 v[106:107], v[88:89], v[8:9]
	v_pk_mul_f32 v[108:109], v[86:87], v[6:7]
	s_waitcnt lgkmcnt(0)
	v_pk_mul_f32 v[88:89], v[112:113], v[98:99] op_sel_hi:[1,0]
	v_pk_mul_f32 v[86:87], v[110:111], v[98:99] op_sel_hi:[1,0]
	v_pk_mul_f32 v[102:103], v[92:93], v[12:13]
	v_pk_mul_f32 v[104:105], v[90:91], v[10:11]
	v_pk_mul_f32 v[92:93], v[158:159], v[98:99] op_sel_hi:[1,0]
	v_pk_mul_f32 v[90:91], v[160:161], v[98:99] op_sel_hi:[1,0]
	v_pk_mul_f32 v[96:97], v[162:163], v[98:99] op_sel_hi:[1,0]
	v_pk_mul_f32 v[94:95], v[164:165], v[98:99] op_sel_hi:[1,0]
	v_pk_mul_f32 v[100:101], v[166:167], v[98:99] op_sel_hi:[1,0]
	v_pk_mul_f32 v[98:99], v[168:169], v[98:99] op_sel_hi:[1,0]
	flat_store_dwordx4 v[150:151], v[86:89] nt
	flat_store_dwordx4 v[150:151], v[90:93] offset:16 nt
	flat_store_dwordx4 v[150:151], v[94:97] offset:512 nt
	flat_store_dwordx4 v[150:151], v[98:101] offset:528 nt
	ds_read_b32 v90, v219
	v_pk_mul_f32 v[92:93], v[84:85], v[4:5]
	v_pk_mul_f32 v[94:95], v[82:83], v[2:3]
	v_pk_mul_f32 v[96:97], v[80:81], v[16:17]
	v_pk_mul_f32 v[98:99], v[78:79], v[14:15]
	s_waitcnt lgkmcnt(0)
	v_pk_mul_f32 v[80:81], v[170:171], v[90:91] op_sel_hi:[1,0]
	v_pk_mul_f32 v[78:79], v[172:173], v[90:91] op_sel_hi:[1,0]
	v_pk_mul_f32 v[84:85], v[102:103], v[90:91] op_sel_hi:[1,0]
	v_pk_mul_f32 v[82:83], v[104:105], v[90:91] op_sel_hi:[1,0]
	v_pk_mul_f32 v[88:89], v[106:107], v[90:91] op_sel_hi:[1,0]
	v_pk_mul_f32 v[86:87], v[108:109], v[90:91] op_sel_hi:[1,0]
	v_pk_mul_f32 v[92:93], v[92:93], v[90:91] op_sel_hi:[1,0]
	v_pk_mul_f32 v[90:91], v[94:95], v[90:91] op_sel_hi:[1,0]
	flat_store_dwordx4 v[152:153], v[78:81] nt
	flat_store_dwordx4 v[152:153], v[82:85] offset:16 nt
	flat_store_dwordx4 v[152:153], v[86:89] offset:512 nt
	flat_store_dwordx4 v[152:153], v[90:93] offset:528 nt
	ds_read_b32 v82, v240
	v_pk_mul_f32 v[68:69], v[68:69], v[4:5]
	v_pk_mul_f32 v[66:67], v[66:67], v[2:3]
	v_pk_mul_f32 v[76:77], v[76:77], v[12:13]
	v_pk_mul_f32 v[74:75], v[74:75], v[10:11]
	v_pk_mul_f32 v[78:79], v[72:73], v[8:9]
	v_pk_mul_f32 v[84:85], v[70:71], v[6:7]
	s_waitcnt lgkmcnt(0)
;     __device__ __forceinline__ void operator()(f32x4 (&acc)[2][2][4][2], const Unit& u, int wr, int wc, int fr, int fq) const {
;     ...
; #pragma unroll
;         for (int ai = 0; ai < 2; ++ai)
; #pragma unroll
;             for (int m = 0; m < 4; ++m) { const int rl = ai * HALF + wr * 64 + m * 16 + fr; const float rs = rstab[rl]; float* orow = out + (size_t)(u.pm * BM + rl) * D + col0;
; #pragma unroll
;                 for (int bj = 0; bj < 2; ++bj) { *(f32x4*)(orow + bj * HALF) = acc[ai][bj][m][0] * gg[bj][0] * rs; *(f32x4*)(orow + bj * HALF + 4) = acc[ai][bj][m][1] * gg[bj][1] * rs; } }
; template <class Epi, bool ALIGN_EPI>
; __device__ __forceinline__ void gemm_phase(LAS unsigned char* lds, const Gemm g, const StaticOrder& S, const Epi& E) {
;     ...
;         if (!has_next) break;
	v_pk_mul_f32 v[72:73], v[96:97], v[82:83] op_sel_hi:[1,0]
	v_pk_mul_f32 v[70:71], v[98:99], v[82:83] op_sel_hi:[1,0]
	v_pk_mul_f32 v[68:69], v[68:69], v[82:83] op_sel_hi:[1,0]
	v_pk_mul_f32 v[66:67], v[66:67], v[82:83] op_sel_hi:[1,0]
	v_pk_mul_f32 v[76:77], v[76:77], v[82:83] op_sel_hi:[1,0]
	v_pk_mul_f32 v[74:75], v[74:75], v[82:83] op_sel_hi:[1,0]
	v_pk_mul_f32 v[80:81], v[78:79], v[82:83] op_sel_hi:[1,0]
	v_pk_mul_f32 v[78:79], v[84:85], v[82:83] op_sel_hi:[1,0]
	flat_store_dwordx4 v[154:155], v[70:73] nt
	flat_store_dwordx4 v[154:155], v[74:77] offset:16 nt
	flat_store_dwordx4 v[154:155], v[78:81] offset:512 nt
	flat_store_dwordx4 v[154:155], v[66:69] offset:528 nt
	ds_read_b32 v66, v241
	v_pk_mul_f32 v[64:65], v[64:65], v[16:17]
	v_add_u32_e32 v68, s51, v213
	v_ashrrev_i32_e32 v69, 31, v68
	v_lshlrev_b64 v[68:69], 12, v[68:69]
	v_lshl_add_u64 v[68:69], s[34:35], 0, v[68:69]
	v_pk_mul_f32 v[62:63], v[62:63], v[14:15]
	v_pk_mul_f32 v[60:61], v[60:61], v[12:13]
	v_pk_mul_f32 v[58:59], v[58:59], v[10:11]
	v_pk_mul_f32 v[56:57], v[56:57], v[8:9]
	v_pk_mul_f32 v[54:55], v[54:55], v[6:7]
	v_pk_mul_f32 v[52:53], v[52:53], v[4:5]
	v_pk_mul_f32 v[50:51], v[50:51], v[2:3]
	v_lshl_add_u64 v[68:69], v[68:69], 0, v[146:147]
	s_waitcnt lgkmcnt(0)
	v_pk_mul_f32 v[64:65], v[64:65], v[66:67] op_sel_hi:[1,0]
	v_pk_mul_f32 v[62:63], v[62:63], v[66:67] op_sel_hi:[1,0]
	v_pk_mul_f32 v[60:61], v[60:61], v[66:67] op_sel_hi:[1,0]
	v_pk_mul_f32 v[58:59], v[58:59], v[66:67] op_sel_hi:[1,0]
	v_pk_mul_f32 v[56:57], v[56:57], v[66:67] op_sel_hi:[1,0]
	v_pk_mul_f32 v[54:55], v[54:55], v[66:67] op_sel_hi:[1,0]
	v_pk_mul_f32 v[52:53], v[52:53], v[66:67] op_sel_hi:[1,0]
	v_pk_mul_f32 v[50:51], v[50:51], v[66:67] op_sel_hi:[1,0]
	flat_store_dwordx4 v[68:69], v[62:65] nt
	flat_store_dwordx4 v[68:69], v[58:61] offset:16 nt
	flat_store_dwordx4 v[68:69], v[54:57] offset:512 nt
	flat_store_dwordx4 v[68:69], v[50:53] offset:528 nt
	ds_read_b32 v50, v242
	v_pk_mul_f32 v[48:49], v[48:49], v[16:17]
	v_add_u32_e32 v52, s51, v214
	v_ashrrev_i32_e32 v53, 31, v52
	v_lshlrev_b64 v[52:53], 12, v[52:53]
	v_lshl_add_u64 v[52:53], s[34:35], 0, v[52:53]
	v_pk_mul_f32 v[46:47], v[46:47], v[14:15]
	v_pk_mul_f32 v[44:45], v[44:45], v[12:13]
	v_pk_mul_f32 v[42:43], v[42:43], v[10:11]
	v_pk_mul_f32 v[40:41], v[40:41], v[8:9]
	v_pk_mul_f32 v[38:39], v[38:39], v[6:7]
	v_pk_mul_f32 v[36:37], v[36:37], v[4:5]
	v_pk_mul_f32 v[34:35], v[34:35], v[2:3]
	v_lshl_add_u64 v[52:53], v[52:53], 0, v[146:147]
	s_waitcnt lgkmcnt(0)
	v_pk_mul_f32 v[48:49], v[48:49], v[50:51] op_sel_hi:[1,0]
	v_pk_mul_f32 v[46:47], v[46:47], v[50:51] op_sel_hi:[1,0]
	v_pk_mul_f32 v[44:45], v[44:45], v[50:51] op_sel_hi:[1,0]
	v_pk_mul_f32 v[42:43], v[42:43], v[50:51] op_sel_hi:[1,0]
	v_pk_mul_f32 v[40:41], v[40:41], v[50:51] op_sel_hi:[1,0]
	v_pk_mul_f32 v[38:39], v[38:39], v[50:51] op_sel_hi:[1,0]
	v_pk_mul_f32 v[36:37], v[36:37], v[50:51] op_sel_hi:[1,0]
	v_pk_mul_f32 v[34:35], v[34:35], v[50:51] op_sel_hi:[1,0]
	flat_store_dwordx4 v[52:53], v[46:49] nt
	flat_store_dwordx4 v[52:53], v[42:45] offset:16 nt
	flat_store_dwordx4 v[52:53], v[38:41] offset:512 nt
	flat_store_dwordx4 v[52:53], v[34:37] offset:528 nt
	ds_read_b32 v34, v243
	v_pk_mul_f32 v[32:33], v[32:33], v[16:17]
	v_add_u32_e32 v36, s51, v215
	v_ashrrev_i32_e32 v37, 31, v36
	v_lshlrev_b64 v[36:37], 12, v[36:37]
	v_lshl_add_u64 v[36:37], s[34:35], 0, v[36:37]
	v_pk_mul_f32 v[30:31], v[30:31], v[14:15]
	v_pk_mul_f32 v[28:29], v[28:29], v[12:13]
	v_pk_mul_f32 v[26:27], v[26:27], v[10:11]
	v_pk_mul_f32 v[24:25], v[24:25], v[8:9]
	v_pk_mul_f32 v[22:23], v[22:23], v[6:7]
	v_pk_mul_f32 v[20:21], v[20:21], v[4:5]
	v_pk_mul_f32 v[18:19], v[18:19], v[2:3]
	v_lshl_add_u64 v[36:37], v[36:37], 0, v[146:147]
	s_waitcnt lgkmcnt(0)
	v_pk_mul_f32 v[32:33], v[32:33], v[34:35] op_sel_hi:[1,0]
	v_pk_mul_f32 v[30:31], v[30:31], v[34:35] op_sel_hi:[1,0]
	v_pk_mul_f32 v[28:29], v[28:29], v[34:35] op_sel_hi:[1,0]
	v_pk_mul_f32 v[26:27], v[26:27], v[34:35] op_sel_hi:[1,0]
	v_pk_mul_f32 v[24:25], v[24:25], v[34:35] op_sel_hi:[1,0]
	v_pk_mul_f32 v[22:23], v[22:23], v[34:35] op_sel_hi:[1,0]
	v_pk_mul_f32 v[20:21], v[20:21], v[34:35] op_sel_hi:[1,0]
	v_pk_mul_f32 v[18:19], v[18:19], v[34:35] op_sel_hi:[1,0]
	flat_store_dwordx4 v[36:37], v[30:33] nt
	flat_store_dwordx4 v[36:37], v[26:29] offset:16 nt
	flat_store_dwordx4 v[36:37], v[22:25] offset:512 nt
	flat_store_dwordx4 v[36:37], v[18:21] offset:528 nt
	ds_read_b32 v18, v244
	v_pk_mul_f32 v[16:17], v[132:133], v[16:17]
	v_add_u32_e32 v20, s51, v216
	v_ashrrev_i32_e32 v21, 31, v20
	v_lshlrev_b64 v[20:21], 12, v[20:21]
	v_lshl_add_u64 v[20:21], s[34:35], 0, v[20:21]
	v_pk_mul_f32 v[14:15], v[136:137], v[14:15]
	v_pk_mul_f32 v[12:13], v[130:131], v[12:13]
	v_pk_mul_f32 v[10:11], v[134:135], v[10:11]
	v_pk_mul_f32 v[8:9], v[138:139], v[8:9]
	v_pk_mul_f32 v[6:7], v[142:143], v[6:7]
	v_pk_mul_f32 v[4:5], v[140:141], v[4:5]
	v_pk_mul_f32 v[2:3], v[144:145], v[2:3]
	v_lshl_add_u64 v[20:21], v[20:21], 0, v[146:147]
	s_waitcnt lgkmcnt(0)
	v_pk_mul_f32 v[16:17], v[16:17], v[18:19] op_sel_hi:[1,0]
	v_pk_mul_f32 v[14:15], v[14:15], v[18:19] op_sel_hi:[1,0]
	v_pk_mul_f32 v[12:13], v[12:13], v[18:19] op_sel_hi:[1,0]
	v_pk_mul_f32 v[10:11], v[10:11], v[18:19] op_sel_hi:[1,0]
	v_pk_mul_f32 v[8:9], v[8:9], v[18:19] op_sel_hi:[1,0]
	v_pk_mul_f32 v[6:7], v[6:7], v[18:19] op_sel_hi:[1,0]
	v_pk_mul_f32 v[4:5], v[4:5], v[18:19] op_sel_hi:[1,0]
	v_pk_mul_f32 v[2:3], v[2:3], v[18:19] op_sel_hi:[1,0]
	flat_store_dwordx4 v[20:21], v[14:17] nt
	flat_store_dwordx4 v[20:21], v[10:13] offset:16 nt
	flat_store_dwordx4 v[20:21], v[6:9] offset:512 nt
	flat_store_dwordx4 v[20:21], v[2:5] offset:528 nt
	s_cbranch_vccnz .LBB0_189
	v_readlane_b32 s4, v255, 2
	v_readlane_b32 s5, v255, 3
	s_andn2_b64 vcc, exec, s[4:5]
	s_cbranch_vccnz .LBB0_188
	s_barrier
	s_branch .LBB0_188
